# seams 4 and 5 (GEMM2->GEMM3, GEMM3->LayerNorm: producer and consumer rows share an XCD, verified at run time from HW_REG_XCC_ID): grid-wide arrive/release kept, L2 write-back skipped, L1-only invalida
# speedup vs baseline: 1.0300x; 1.0247x over previous
; __device__ __forceinline__ unsigned cvt_pk_bf16(float lo, float hi) { unsigned r; asm volatile("v_cvt_pk_bf16_f32 %0, %1, %2" : "=v"(r) : "v"(lo), "v"(hi)); return r; }
; __global__ void __launch_bounds__(512, 2) hybrid_fwd(Args a) {
;     ...
;     if (bx == 0 && tid < 72) __hip_atomic_store((unsigned*)(ws + WS_CTL) + 1024 * (tid / 9) + 64 * (tid % 9), 0u, __ATOMIC_RELAXED, __HIP_MEMORY_SCOPE_AGENT);
;     {
;         const size_t gt = (size_t)bx * 512 + tid, GT = (size_t)G * 512;
;         {
;             const size_t NCH = (size_t)M * D / 8;
;             for (size_t i0 = gt; i0 < NCH; i0 += 4 * GT) {
;                 f32x4 v[4][2];
; #pragma unroll
;                 for (int u = 0; u < 4; ++u) { const size_t i = i0 + (size_t)u * GT; if (i < NCH) { v[u][0] = ((const f32x4*)a.x)[2 * i]; v[u][1] = ((const f32x4*)a.x)[2 * i + 1]; } }
; #pragma unroll
;                 for (int u = 0; u < 4; ++u) { const size_t i = i0 + (size_t)u * GT; if (i < NCH) {
;                     u32x4 w; w.x = cvt_pk_bf16(v[u][0][0], v[u][0][1]); w.y = cvt_pk_bf16(v[u][0][2], v[u][0][3]); w.z = cvt_pk_bf16(v[u][1][0], v[u][1][1]); w.w = cvt_pk_bf16(v[u][1][2], v[u][1][3]);
;                     if (a.n_bf16 > 0) ((u32x4*)XB)[i] = w;
;                     const unsigned p0 = pack_fp8x4(v[u][0][0], v[u][0][1], v[u][0][2], v[u][0][3]), p1 = pack_fp8x4(v[u][1][0], v[u][1][1], v[u][1][2], v[u][1][3]);
;                     ((u32x2*)XB8)[i] = (u32x2){p0, p1}; } }
.LBB0_2:
	s_or_b64 exec, exec, s[4:5]
	v_cmp_eq_u32_e32 vcc, 0, v160
	s_and_saveexec_b64 s[4:5], vcc
	s_lshl_b32 s100, s2, 12
	s_add_u32 s100, s100, 0x8e10000
	v_mov_b32_e32 v243, s100
	v_mov_b32_e32 v244, 0
	s_waitcnt lgkmcnt(0)
	global_store_dword v243, v244, s[90:91] sc1
	s_getreg_b32 s100, hwreg(HW_REG_XCC_ID, 0, 4)
	v_mov_b32_e32 v244, s100
	s_lshl_b32 s100, s2, 2
	s_add_u32 s100, s100, 0x8e08000
	v_mov_b32_e32 v243, s100
	global_store_dword v243, v244, s[90:91] sc1
	s_or_b64 exec, exec, s[4:5]
	s_ashr_i32 s3, s2, 31
	s_lshl_b64 s[4:5], s[2:3], 9
	v_mov_b32_e32 v161, 0
	v_lshl_add_u64 v[38:39], s[4:5], 0, v[160:161]
	s_waitcnt lgkmcnt(0)
	s_ashr_i32 s93, s92, 31
	s_mov_b64 s[12:13], 0x400000
	s_lshl_b64 s[14:15], s[92:93], 9
	v_cmp_gt_u64_e32 vcc, s[12:13], v[38:39]
	v_lshlrev_b32_e32 v40, 3, v160
	s_mov_b32 s100, 0
	s_cmp_lg_u32 s92, 0x100
	s_cbranch_scc1 .Lp0_done
	s_load_dword s16, s[70:71], 0x1c0
	s_load_dwordx2 s[18:19], s[70:71], 0x1c8
	s_load_dwordx2 s[6:7], s[70:71], 0x0
	s_load_dwordx2 s[20:21], s[70:71], 0x8
	s_load_dwordx2 s[22:23], s[70:71], 0x10
	s_waitcnt lgkmcnt(0)
	s_cmp_lg_u32 s16, 0
	s_cbranch_scc1 .Lp0_done
	s_cmp_lg_u32 s18, -1
	s_cbranch_scc1 .Lp0_done
	s_cmpk_lg_u32 s19, 0x1fff
	s_cbranch_scc1 .Lp0_done
	v_lshl_add_u32 v1, s2, 9, v160
	v_and_b32_e32 v4, 63, v160
	v_lshlrev_b32_e32 v2, 5, v1
	v_lshlrev_b32_e32 v3, 3, v1
	s_mov_b64 s[8:9], s[88:89]
	global_load_dwordx4 v[64:67], v2, s[6:7] nt
	global_load_dwordx4 v[68:71], v2, s[6:7] offset:16 nt
	s_add_u32 s6, s6, 0x400000
	s_addc_u32 s7, s7, 0
	global_load_dwordx4 v[72:75], v2, s[6:7] nt
	global_load_dwordx4 v[76:79], v2, s[6:7] offset:16 nt
	s_add_u32 s6, s6, 0x400000
	s_addc_u32 s7, s7, 0
	global_load_dwordx4 v[80:83], v2, s[6:7] nt
	global_load_dwordx4 v[84:87], v2, s[6:7] offset:16 nt
	s_add_u32 s6, s6, 0x400000
	s_addc_u32 s7, s7, 0
	global_load_dwordx4 v[88:91], v2, s[6:7] nt
	global_load_dwordx4 v[92:95], v2, s[6:7] offset:16 nt
	s_add_u32 s6, s6, 0x400000
	s_addc_u32 s7, s7, 0
	global_load_dwordx4 v[96:99], v2, s[6:7] nt
	global_load_dwordx4 v[100:103], v2, s[6:7] offset:16 nt
	s_add_u32 s6, s6, 0x400000
	s_addc_u32 s7, s7, 0
	global_load_dwordx4 v[104:107], v2, s[6:7] nt
	global_load_dwordx4 v[108:111], v2, s[6:7] offset:16 nt
	s_add_u32 s6, s6, 0x400000
	s_addc_u32 s7, s7, 0
	global_load_dwordx4 v[112:115], v2, s[6:7] nt
	global_load_dwordx4 v[116:119], v2, s[6:7] offset:16 nt
	s_add_u32 s6, s6, 0x400000
	s_addc_u32 s7, s7, 0
	global_load_dwordx4 v[120:123], v2, s[6:7] nt
	global_load_dwordx4 v[124:127], v2, s[6:7] offset:16 nt
	s_add_u32 s6, s6, 0x400000
	s_addc_u32 s7, s7, 0
	s_waitcnt vmcnt(14)
	v_cvt_pk_fp8_f32 v8, v64, v65
	v_cvt_pk_fp8_f32 v9, v66, v67
	v_cvt_pk_fp8_f32 v10, v68, v69
	v_cvt_pk_fp8_f32 v11, v70, v71
	v_and_b32_e32 v8, 0xffff, v8
	v_and_b32_e32 v10, 0xffff, v10
	v_lshl_or_b32 v128, v9, 16, v8
	v_lshl_or_b32 v129, v11, 16, v10
	global_store_dwordx2 v3, v[128:129], s[8:9]
	s_add_u32 s8, s8, 0x100000
	s_addc_u32 s9, s9, 0
	global_load_dwordx4 v[64:67], v2, s[6:7] nt
	global_load_dwordx4 v[68:71], v2, s[6:7] offset:16 nt
	s_add_u32 s6, s6, 0x400000
	s_addc_u32 s7, s7, 0
	s_waitcnt vmcnt(15)
	v_cvt_pk_fp8_f32 v8, v72, v73
	v_cvt_pk_fp8_f32 v9, v74, v75
	v_cvt_pk_fp8_f32 v10, v76, v77
	v_cvt_pk_fp8_f32 v11, v78, v79
	v_and_b32_e32 v8, 0xffff, v8
	v_and_b32_e32 v10, 0xffff, v10
	v_lshl_or_b32 v130, v9, 16, v8
	v_lshl_or_b32 v131, v11, 16, v10
	global_store_dwordx2 v3, v[130:131], s[8:9]
	s_add_u32 s8, s8, 0x100000
	s_addc_u32 s9, s9, 0
	global_load_dwordx4 v[72:75], v2, s[6:7] nt
	global_load_dwordx4 v[76:79], v2, s[6:7] offset:16 nt
	s_add_u32 s6, s6, 0x400000
	s_addc_u32 s7, s7, 0
	s_waitcnt vmcnt(16)
	v_cvt_pk_fp8_f32 v8, v80, v81
	v_cvt_pk_fp8_f32 v9, v82, v83
	v_cvt_pk_fp8_f32 v10, v84, v85
	v_cvt_pk_fp8_f32 v11, v86, v87
	v_and_b32_e32 v8, 0xffff, v8
	v_and_b32_e32 v10, 0xffff, v10
	v_lshl_or_b32 v132, v9, 16, v8
	v_lshl_or_b32 v133, v11, 16, v10
	global_store_dwordx2 v3, v[132:133], s[8:9]
	s_add_u32 s8, s8, 0x100000
	s_addc_u32 s9, s9, 0
	global_load_dwordx4 v[80:83], v2, s[6:7] nt
	global_load_dwordx4 v[84:87], v2, s[6:7] offset:16 nt
	s_add_u32 s6, s6, 0x400000
	s_addc_u32 s7, s7, 0
	s_waitcnt vmcnt(17)
	v_cvt_pk_fp8_f32 v8, v88, v89
	v_cvt_pk_fp8_f32 v9, v90, v91
	v_cvt_pk_fp8_f32 v10, v92, v93
	v_cvt_pk_fp8_f32 v11, v94, v95
	v_and_b32_e32 v8, 0xffff, v8
	v_and_b32_e32 v10, 0xffff, v10
	v_lshl_or_b32 v134, v9, 16, v8
	v_lshl_or_b32 v135, v11, 16, v10
	global_store_dwordx2 v3, v[134:135], s[8:9]
	s_add_u32 s8, s8, 0x100000
	s_addc_u32 s9, s9, 0
	global_load_dwordx4 v[88:91], v2, s[6:7] nt
	global_load_dwordx4 v[92:95], v2, s[6:7] offset:16 nt
	s_add_u32 s6, s6, 0x400000
	s_addc_u32 s7, s7, 0
	s_waitcnt vmcnt(18)
	v_cvt_pk_fp8_f32 v8, v96, v97
	v_cvt_pk_fp8_f32 v9, v98, v99
	v_cvt_pk_fp8_f32 v10, v100, v101
	v_cvt_pk_fp8_f32 v11, v102, v103
	v_and_b32_e32 v8, 0xffff, v8
	v_and_b32_e32 v10, 0xffff, v10
	v_lshl_or_b32 v136, v9, 16, v8
	v_lshl_or_b32 v137, v11, 16, v10
	global_store_dwordx2 v3, v[136:137], s[8:9]
	s_add_u32 s8, s8, 0x100000
	s_addc_u32 s9, s9, 0
	global_load_dwordx4 v[96:99], v2, s[6:7] nt
	global_load_dwordx4 v[100:103], v2, s[6:7] offset:16 nt
	s_add_u32 s6, s6, 0x400000
	s_addc_u32 s7, s7, 0
	s_waitcnt vmcnt(19)
	v_cvt_pk_fp8_f32 v8, v104, v105
	v_cvt_pk_fp8_f32 v9, v106, v107
	v_cvt_pk_fp8_f32 v10, v108, v109
	v_cvt_pk_fp8_f32 v11, v110, v111
	v_and_b32_e32 v8, 0xffff, v8
	v_and_b32_e32 v10, 0xffff, v10
	v_lshl_or_b32 v138, v9, 16, v8
	v_lshl_or_b32 v139, v11, 16, v10
	global_store_dwordx2 v3, v[138:139], s[8:9]
	s_add_u32 s8, s8, 0x100000
	s_addc_u32 s9, s9, 0
	global_load_dwordx4 v[104:107], v2, s[6:7] nt
	global_load_dwordx4 v[108:111], v2, s[6:7] offset:16 nt
	s_add_u32 s6, s6, 0x400000
	s_addc_u32 s7, s7, 0
	s_waitcnt vmcnt(20)
; __device__ __forceinline__ unsigned cvt_pk_bf16(float lo, float hi) { unsigned r; asm volatile("v_cvt_pk_bf16_f32 %0, %1, %2" : "=v"(r) : "v"(lo), "v"(hi)); return r; }
; __global__ void __launch_bounds__(512, 2) hybrid_fwd(Args a) {
;     ...
;             for (size_t i0 = gt; i0 < NCH; i0 += 4 * GT) {
;                 f32x4 v[4][2];
; #pragma unroll
;                 for (int u = 0; u < 4; ++u) { const size_t i = i0 + (size_t)u * GT; if (i < NCH) { v[u][0] = ((const f32x4*)a.x)[2 * i]; v[u][1] = ((const f32x4*)a.x)[2 * i + 1]; } }
; #pragma unroll
;                 for (int u = 0; u < 4; ++u) { const size_t i = i0 + (size_t)u * GT; if (i < NCH) {
;                     u32x4 w; w.x = cvt_pk_bf16(v[u][0][0], v[u][0][1]); w.y = cvt_pk_bf16(v[u][0][2], v[u][0][3]); w.z = cvt_pk_bf16(v[u][1][0], v[u][1][1]); w.w = cvt_pk_bf16(v[u][1][2], v[u][1][3]);
;                     if (a.n_bf16 > 0) ((u32x4*)XB)[i] = w;
;                     const unsigned p0 = pack_fp8x4(v[u][0][0], v[u][0][1], v[u][0][2], v[u][0][3]), p1 = pack_fp8x4(v[u][1][0], v[u][1][1], v[u][1][2], v[u][1][3]);
;                     ((u32x2*)XB8)[i] = (u32x2){p0, p1}; } }
	v_cvt_pk_fp8_f32 v8, v112, v113
	v_cvt_pk_fp8_f32 v9, v114, v115
	v_cvt_pk_fp8_f32 v10, v116, v117
	v_cvt_pk_fp8_f32 v11, v118, v119
	v_and_b32_e32 v8, 0xffff, v8
	v_and_b32_e32 v10, 0xffff, v10
	v_lshl_or_b32 v140, v9, 16, v8
	v_lshl_or_b32 v141, v11, 16, v10
	global_store_dwordx2 v3, v[140:141], s[8:9]
	s_add_u32 s8, s8, 0x100000
	s_addc_u32 s9, s9, 0
	global_load_dwordx4 v[112:115], v2, s[6:7] nt
	global_load_dwordx4 v[116:119], v2, s[6:7] offset:16 nt
	s_add_u32 s6, s6, 0x400000
	s_addc_u32 s7, s7, 0
	s_waitcnt vmcnt(21)
	v_cvt_pk_fp8_f32 v8, v120, v121
	v_cvt_pk_fp8_f32 v9, v122, v123
	v_cvt_pk_fp8_f32 v10, v124, v125
	v_cvt_pk_fp8_f32 v11, v126, v127
	v_and_b32_e32 v8, 0xffff, v8
	v_and_b32_e32 v10, 0xffff, v10
	v_lshl_or_b32 v142, v9, 16, v8
	v_lshl_or_b32 v143, v11, 16, v10
	global_store_dwordx2 v3, v[142:143], s[8:9]
	s_add_u32 s8, s8, 0x100000
	s_addc_u32 s9, s9, 0
	global_load_dwordx4 v[120:123], v2, s[6:7] nt
	global_load_dwordx4 v[124:127], v2, s[6:7] offset:16 nt
	s_add_u32 s6, s6, 0x400000
	s_addc_u32 s7, s7, 0
	s_waitcnt vmcnt(21)
	v_cvt_pk_fp8_f32 v8, v64, v65
	v_cvt_pk_fp8_f32 v9, v66, v67
	v_cvt_pk_fp8_f32 v10, v68, v69
	v_cvt_pk_fp8_f32 v11, v70, v71
	v_and_b32_e32 v8, 0xffff, v8
	v_and_b32_e32 v10, 0xffff, v10
	v_lshl_or_b32 v128, v9, 16, v8
	v_lshl_or_b32 v129, v11, 16, v10
	global_store_dwordx2 v3, v[128:129], s[8:9]
	s_add_u32 s8, s8, 0x100000
	s_addc_u32 s9, s9, 0
	global_load_dwordx4 v[64:67], v2, s[6:7] nt
	global_load_dwordx4 v[68:71], v2, s[6:7] offset:16 nt
	s_add_u32 s6, s6, 0x400000
	s_addc_u32 s7, s7, 0
	s_waitcnt vmcnt(21)
	v_cvt_pk_fp8_f32 v8, v72, v73
	v_cvt_pk_fp8_f32 v9, v74, v75
	v_cvt_pk_fp8_f32 v10, v76, v77
	v_cvt_pk_fp8_f32 v11, v78, v79
	v_and_b32_e32 v8, 0xffff, v8
	v_and_b32_e32 v10, 0xffff, v10
	v_lshl_or_b32 v130, v9, 16, v8
	v_lshl_or_b32 v131, v11, 16, v10
	global_store_dwordx2 v3, v[130:131], s[8:9]
	s_add_u32 s8, s8, 0x100000
	s_addc_u32 s9, s9, 0
	global_load_dwordx4 v[72:75], v2, s[6:7] nt
	global_load_dwordx4 v[76:79], v2, s[6:7] offset:16 nt
	s_add_u32 s6, s6, 0x400000
	s_addc_u32 s7, s7, 0
	s_waitcnt vmcnt(21)
	v_cvt_pk_fp8_f32 v8, v80, v81
	v_cvt_pk_fp8_f32 v9, v82, v83
	v_cvt_pk_fp8_f32 v10, v84, v85
	v_cvt_pk_fp8_f32 v11, v86, v87
	v_and_b32_e32 v8, 0xffff, v8
	v_and_b32_e32 v10, 0xffff, v10
	v_lshl_or_b32 v132, v9, 16, v8
	v_lshl_or_b32 v133, v11, 16, v10
	global_store_dwordx2 v3, v[132:133], s[8:9]
	s_add_u32 s8, s8, 0x100000
	s_addc_u32 s9, s9, 0
	global_load_dwordx4 v[80:83], v2, s[6:7] nt
	global_load_dwordx4 v[84:87], v2, s[6:7] offset:16 nt
	s_add_u32 s6, s6, 0x400000
	s_addc_u32 s7, s7, 0
	s_waitcnt vmcnt(21)
	v_cvt_pk_fp8_f32 v8, v88, v89
	v_cvt_pk_fp8_f32 v9, v90, v91
	v_cvt_pk_fp8_f32 v10, v92, v93
	v_cvt_pk_fp8_f32 v11, v94, v95
	v_and_b32_e32 v8, 0xffff, v8
	v_and_b32_e32 v10, 0xffff, v10
	v_lshl_or_b32 v134, v9, 16, v8
	v_lshl_or_b32 v135, v11, 16, v10
	global_store_dwordx2 v3, v[134:135], s[8:9]
	s_add_u32 s8, s8, 0x100000
	s_addc_u32 s9, s9, 0
	global_load_dwordx4 v[88:91], v2, s[6:7] nt
	global_load_dwordx4 v[92:95], v2, s[6:7] offset:16 nt
	s_add_u32 s6, s6, 0x400000
	s_addc_u32 s7, s7, 0
	s_waitcnt vmcnt(21)
	v_cvt_pk_fp8_f32 v8, v96, v97
	v_cvt_pk_fp8_f32 v9, v98, v99
	v_cvt_pk_fp8_f32 v10, v100, v101
	v_cvt_pk_fp8_f32 v11, v102, v103
	v_and_b32_e32 v8, 0xffff, v8
	v_and_b32_e32 v10, 0xffff, v10
	v_lshl_or_b32 v136, v9, 16, v8
	v_lshl_or_b32 v137, v11, 16, v10
	global_store_dwordx2 v3, v[136:137], s[8:9]
	s_add_u32 s8, s8, 0x100000
	s_addc_u32 s9, s9, 0
	global_load_dwordx4 v[96:99], v2, s[6:7] nt
	global_load_dwordx4 v[100:103], v2, s[6:7] offset:16 nt
	s_add_u32 s6, s6, 0x400000
	s_addc_u32 s7, s7, 0
	s_waitcnt vmcnt(21)
	v_cvt_pk_fp8_f32 v8, v104, v105
	v_cvt_pk_fp8_f32 v9, v106, v107
	v_cvt_pk_fp8_f32 v10, v108, v109
	v_cvt_pk_fp8_f32 v11, v110, v111
	v_and_b32_e32 v8, 0xffff, v8
	v_and_b32_e32 v10, 0xffff, v10
	v_lshl_or_b32 v138, v9, 16, v8
	v_lshl_or_b32 v139, v11, 16, v10
	global_store_dwordx2 v3, v[138:139], s[8:9]
	s_add_u32 s8, s8, 0x100000
	s_addc_u32 s9, s9, 0
	global_load_dwordx4 v[104:107], v2, s[6:7] nt
	global_load_dwordx4 v[108:111], v2, s[6:7] offset:16 nt
	s_add_u32 s6, s6, 0x400000
	s_addc_u32 s7, s7, 0
	s_waitcnt vmcnt(21)
	v_cvt_pk_fp8_f32 v8, v112, v113
	v_cvt_pk_fp8_f32 v9, v114, v115
	v_cvt_pk_fp8_f32 v10, v116, v117
	v_cvt_pk_fp8_f32 v11, v118, v119
	v_and_b32_e32 v8, 0xffff, v8
	v_and_b32_e32 v10, 0xffff, v10
	v_lshl_or_b32 v140, v9, 16, v8
	v_lshl_or_b32 v141, v11, 16, v10
	global_store_dwordx2 v3, v[140:141], s[8:9]
	s_add_u32 s8, s8, 0x100000
	s_addc_u32 s9, s9, 0
	global_load_dwordx4 v[112:115], v2, s[6:7] nt
	global_load_dwordx4 v[116:119], v2, s[6:7] offset:16 nt
	s_add_u32 s6, s6, 0x400000
	s_addc_u32 s7, s7, 0
	s_waitcnt vmcnt(21)
	v_cvt_pk_fp8_f32 v8, v120, v121
	v_cvt_pk_fp8_f32 v9, v122, v123
	v_cvt_pk_fp8_f32 v10, v124, v125
	v_cvt_pk_fp8_f32 v11, v126, v127
	v_and_b32_e32 v8, 0xffff, v8
	v_and_b32_e32 v10, 0xffff, v10
	v_lshl_or_b32 v142, v9, 16, v8
	v_lshl_or_b32 v143, v11, 16, v10
	global_store_dwordx2 v3, v[142:143], s[8:9]
	s_add_u32 s8, s8, 0x100000
	s_addc_u32 s9, s9, 0
	global_load_dwordx4 v[120:123], v2, s[6:7] nt
	global_load_dwordx4 v[124:127], v2, s[6:7] offset:16 nt
	s_add_u32 s6, s6, 0x400000
	s_addc_u32 s7, s7, 0
	s_waitcnt vmcnt(21)
	v_cvt_pk_fp8_f32 v8, v64, v65
	v_cvt_pk_fp8_f32 v9, v66, v67
	v_cvt_pk_fp8_f32 v10, v68, v69
	v_cvt_pk_fp8_f32 v11, v70, v71
	v_and_b32_e32 v8, 0xffff, v8
	v_and_b32_e32 v10, 0xffff, v10
	v_lshl_or_b32 v128, v9, 16, v8
	v_lshl_or_b32 v129, v11, 16, v10
	global_store_dwordx2 v3, v[128:129], s[8:9]
	s_add_u32 s8, s8, 0x100000
	s_addc_u32 s9, s9, 0
	global_load_dwordx4 v[64:67], v2, s[6:7] nt
	global_load_dwordx4 v[68:71], v2, s[6:7] offset:16 nt
	s_add_u32 s6, s6, 0x400000
	s_addc_u32 s7, s7, 0
	s_waitcnt vmcnt(21)
; __device__ __forceinline__ unsigned cvt_pk_bf16(float lo, float hi) { unsigned r; asm volatile("v_cvt_pk_bf16_f32 %0, %1, %2" : "=v"(r) : "v"(lo), "v"(hi)); return r; }
; __global__ void __launch_bounds__(512, 2) hybrid_fwd(Args a) {
;     ...
;             for (size_t i0 = gt; i0 < NCH; i0 += 4 * GT) {
;                 f32x4 v[4][2];
; #pragma unroll
;                 for (int u = 0; u < 4; ++u) { const size_t i = i0 + (size_t)u * GT; if (i < NCH) { v[u][0] = ((const f32x4*)a.x)[2 * i]; v[u][1] = ((const f32x4*)a.x)[2 * i + 1]; } }
; #pragma unroll
;                 for (int u = 0; u < 4; ++u) { const size_t i = i0 + (size_t)u * GT; if (i < NCH) {
;                     u32x4 w; w.x = cvt_pk_bf16(v[u][0][0], v[u][0][1]); w.y = cvt_pk_bf16(v[u][0][2], v[u][0][3]); w.z = cvt_pk_bf16(v[u][1][0], v[u][1][1]); w.w = cvt_pk_bf16(v[u][1][2], v[u][1][3]);
;                     if (a.n_bf16 > 0) ((u32x4*)XB)[i] = w;
;                     const unsigned p0 = pack_fp8x4(v[u][0][0], v[u][0][1], v[u][0][2], v[u][0][3]), p1 = pack_fp8x4(v[u][1][0], v[u][1][1], v[u][1][2], v[u][1][3]);
;                     ((u32x2*)XB8)[i] = (u32x2){p0, p1}; } }
	v_cvt_pk_fp8_f32 v8, v72, v73
	v_cvt_pk_fp8_f32 v9, v74, v75
	v_cvt_pk_fp8_f32 v10, v76, v77
	v_cvt_pk_fp8_f32 v11, v78, v79
	v_and_b32_e32 v8, 0xffff, v8
	v_and_b32_e32 v10, 0xffff, v10
	v_lshl_or_b32 v130, v9, 16, v8
	v_lshl_or_b32 v131, v11, 16, v10
	global_store_dwordx2 v3, v[130:131], s[8:9]
	s_add_u32 s8, s8, 0x100000
	s_addc_u32 s9, s9, 0
	global_load_dwordx4 v[72:75], v2, s[6:7] nt
	global_load_dwordx4 v[76:79], v2, s[6:7] offset:16 nt
	s_add_u32 s6, s6, 0x400000
	s_addc_u32 s7, s7, 0
	s_waitcnt vmcnt(21)
	v_cvt_pk_fp8_f32 v8, v80, v81
	v_cvt_pk_fp8_f32 v9, v82, v83
	v_cvt_pk_fp8_f32 v10, v84, v85
	v_cvt_pk_fp8_f32 v11, v86, v87
	v_and_b32_e32 v8, 0xffff, v8
	v_and_b32_e32 v10, 0xffff, v10
	v_lshl_or_b32 v132, v9, 16, v8
	v_lshl_or_b32 v133, v11, 16, v10
	global_store_dwordx2 v3, v[132:133], s[8:9]
	s_add_u32 s8, s8, 0x100000
	s_addc_u32 s9, s9, 0
	global_load_dwordx4 v[80:83], v2, s[6:7] nt
	global_load_dwordx4 v[84:87], v2, s[6:7] offset:16 nt
	s_add_u32 s6, s6, 0x400000
	s_addc_u32 s7, s7, 0
	s_waitcnt vmcnt(21)
	v_cvt_pk_fp8_f32 v8, v88, v89
	v_cvt_pk_fp8_f32 v9, v90, v91
	v_cvt_pk_fp8_f32 v10, v92, v93
	v_cvt_pk_fp8_f32 v11, v94, v95
	v_and_b32_e32 v8, 0xffff, v8
	v_and_b32_e32 v10, 0xffff, v10
	v_lshl_or_b32 v134, v9, 16, v8
	v_lshl_or_b32 v135, v11, 16, v10
	global_store_dwordx2 v3, v[134:135], s[8:9]
	s_add_u32 s8, s8, 0x100000
	s_addc_u32 s9, s9, 0
	global_load_dwordx4 v[88:91], v2, s[6:7] nt
	global_load_dwordx4 v[92:95], v2, s[6:7] offset:16 nt
	s_add_u32 s6, s6, 0x400000
	s_addc_u32 s7, s7, 0
	s_waitcnt vmcnt(21)
	v_cvt_pk_fp8_f32 v8, v96, v97
	v_cvt_pk_fp8_f32 v9, v98, v99
	v_cvt_pk_fp8_f32 v10, v100, v101
	v_cvt_pk_fp8_f32 v11, v102, v103
	v_and_b32_e32 v8, 0xffff, v8
	v_and_b32_e32 v10, 0xffff, v10
	v_lshl_or_b32 v136, v9, 16, v8
	v_lshl_or_b32 v137, v11, 16, v10
	global_store_dwordx2 v3, v[136:137], s[8:9]
	s_add_u32 s8, s8, 0x100000
	s_addc_u32 s9, s9, 0
	global_load_dwordx4 v[96:99], v2, s[6:7] nt
	global_load_dwordx4 v[100:103], v2, s[6:7] offset:16 nt
	s_add_u32 s6, s6, 0x400000
	s_addc_u32 s7, s7, 0
	s_waitcnt vmcnt(21)
	v_cvt_pk_fp8_f32 v8, v104, v105
	v_cvt_pk_fp8_f32 v9, v106, v107
	v_cvt_pk_fp8_f32 v10, v108, v109
	v_cvt_pk_fp8_f32 v11, v110, v111
	v_and_b32_e32 v8, 0xffff, v8
	v_and_b32_e32 v10, 0xffff, v10
	v_lshl_or_b32 v138, v9, 16, v8
	v_lshl_or_b32 v139, v11, 16, v10
	global_store_dwordx2 v3, v[138:139], s[8:9]
	s_add_u32 s8, s8, 0x100000
	s_addc_u32 s9, s9, 0
	global_load_dwordx4 v[104:107], v2, s[6:7] nt
	global_load_dwordx4 v[108:111], v2, s[6:7] offset:16 nt
	s_add_u32 s6, s6, 0x400000
	s_addc_u32 s7, s7, 0
	s_waitcnt vmcnt(21)
	v_cvt_pk_fp8_f32 v8, v112, v113
	v_cvt_pk_fp8_f32 v9, v114, v115
	v_cvt_pk_fp8_f32 v10, v116, v117
	v_cvt_pk_fp8_f32 v11, v118, v119
	v_and_b32_e32 v8, 0xffff, v8
	v_and_b32_e32 v10, 0xffff, v10
	v_lshl_or_b32 v140, v9, 16, v8
	v_lshl_or_b32 v141, v11, 16, v10
	global_store_dwordx2 v3, v[140:141], s[8:9]
	s_add_u32 s8, s8, 0x100000
	s_addc_u32 s9, s9, 0
	global_load_dwordx4 v[112:115], v2, s[6:7] nt
	global_load_dwordx4 v[116:119], v2, s[6:7] offset:16 nt
	s_add_u32 s6, s6, 0x400000
	s_addc_u32 s7, s7, 0
	s_waitcnt vmcnt(21)
	v_cvt_pk_fp8_f32 v8, v120, v121
	v_cvt_pk_fp8_f32 v9, v122, v123
	v_cvt_pk_fp8_f32 v10, v124, v125
	v_cvt_pk_fp8_f32 v11, v126, v127
	v_and_b32_e32 v8, 0xffff, v8
	v_and_b32_e32 v10, 0xffff, v10
	v_lshl_or_b32 v142, v9, 16, v8
	v_lshl_or_b32 v143, v11, 16, v10
	global_store_dwordx2 v3, v[142:143], s[8:9]
	s_add_u32 s8, s8, 0x100000
	s_addc_u32 s9, s9, 0
	global_load_dwordx4 v[120:123], v2, s[6:7] nt
	global_load_dwordx4 v[124:127], v2, s[6:7] offset:16 nt
	s_add_u32 s6, s6, 0x400000
	s_addc_u32 s7, s7, 0
	s_waitcnt vmcnt(21)
	v_cvt_pk_fp8_f32 v8, v64, v65
	v_cvt_pk_fp8_f32 v9, v66, v67
	v_cvt_pk_fp8_f32 v10, v68, v69
	v_cvt_pk_fp8_f32 v11, v70, v71
	v_and_b32_e32 v8, 0xffff, v8
	v_and_b32_e32 v10, 0xffff, v10
	v_lshl_or_b32 v128, v9, 16, v8
	v_lshl_or_b32 v129, v11, 16, v10
	global_store_dwordx2 v3, v[128:129], s[8:9]
	s_add_u32 s8, s8, 0x100000
	s_addc_u32 s9, s9, 0
	s_waitcnt vmcnt(19)
	v_cvt_pk_fp8_f32 v8, v72, v73
	v_cvt_pk_fp8_f32 v9, v74, v75
	v_cvt_pk_fp8_f32 v10, v76, v77
	v_cvt_pk_fp8_f32 v11, v78, v79
	v_and_b32_e32 v8, 0xffff, v8
	v_and_b32_e32 v10, 0xffff, v10
	v_lshl_or_b32 v130, v9, 16, v8
	v_lshl_or_b32 v131, v11, 16, v10
	global_store_dwordx2 v3, v[130:131], s[8:9]
	s_add_u32 s8, s8, 0x100000
	s_addc_u32 s9, s9, 0
	s_waitcnt vmcnt(17)
	v_cvt_pk_fp8_f32 v8, v80, v81
	v_cvt_pk_fp8_f32 v9, v82, v83
	v_cvt_pk_fp8_f32 v10, v84, v85
	v_cvt_pk_fp8_f32 v11, v86, v87
	v_and_b32_e32 v8, 0xffff, v8
	v_and_b32_e32 v10, 0xffff, v10
	v_lshl_or_b32 v132, v9, 16, v8
	v_lshl_or_b32 v133, v11, 16, v10
	global_store_dwordx2 v3, v[132:133], s[8:9]
	s_add_u32 s8, s8, 0x100000
	s_addc_u32 s9, s9, 0
	s_waitcnt vmcnt(15)
	v_cvt_pk_fp8_f32 v8, v88, v89
	v_cvt_pk_fp8_f32 v9, v90, v91
	v_cvt_pk_fp8_f32 v10, v92, v93
	v_cvt_pk_fp8_f32 v11, v94, v95
	v_and_b32_e32 v8, 0xffff, v8
	v_and_b32_e32 v10, 0xffff, v10
	v_lshl_or_b32 v134, v9, 16, v8
	v_lshl_or_b32 v135, v11, 16, v10
	global_store_dwordx2 v3, v[134:135], s[8:9]
	s_add_u32 s8, s8, 0x100000
	s_addc_u32 s9, s9, 0
	s_waitcnt vmcnt(13)
	v_cvt_pk_fp8_f32 v8, v96, v97
	v_cvt_pk_fp8_f32 v9, v98, v99
	v_cvt_pk_fp8_f32 v10, v100, v101
	v_cvt_pk_fp8_f32 v11, v102, v103
	v_and_b32_e32 v8, 0xffff, v8
	v_and_b32_e32 v10, 0xffff, v10
	v_lshl_or_b32 v136, v9, 16, v8
	v_lshl_or_b32 v137, v11, 16, v10
	global_store_dwordx2 v3, v[136:137], s[8:9]
	s_add_u32 s8, s8, 0x100000
	s_addc_u32 s9, s9, 0
	s_waitcnt vmcnt(11)
; __global__ void __launch_bounds__(512, 2) hybrid_fwd(Args a) {
;     ...
;         for (size_t i = gt; i < (size_t)M * 64; i += GT) {
;             const int t = (int)(i >> 6), j = (int)(i & 63);
;             const float ang = (float)a.pos[t] * a.inv_freq[j];
;             const double rev = (double)ang * 0.15915494309189535; const float fr = (float)(rev - __builtin_rint(rev));
;             const f32x2 cs = (f32x2){__builtin_amdgcn_cosf(fr), __builtin_amdgcn_sinf(fr)};
;             csB[i] = cs; if ((j & 1) == 0) csA[(size_t)t * 32 + (j >> 1)] = cs;
;         }
;     ...
;         constexpr int I_IN = (D / 64) * (DIN / 32);
;         for (int it = gw; it < I_IN; it += NGW) { const int nb = it % (DIN / 32), kb = it / (DIN / 32);
;             if ((a.fp8mask >> (nb >> 3)) & 1ull) transpose_item_fp8(a.w_in, DIN, (unsigned char*)WinT, 4096, 0, 64 * kb, gemm_col_to_orig(32 * nb), 32 * nb, W8_SCALE, scr, lane);
	v_cvt_pk_fp8_f32 v8, v104, v105
	v_cvt_pk_fp8_f32 v9, v106, v107
	v_cvt_pk_fp8_f32 v10, v108, v109
	v_cvt_pk_fp8_f32 v11, v110, v111
	v_and_b32_e32 v8, 0xffff, v8
	v_and_b32_e32 v10, 0xffff, v10
	v_lshl_or_b32 v138, v9, 16, v8
	v_lshl_or_b32 v139, v11, 16, v10
	global_store_dwordx2 v3, v[138:139], s[8:9]
	s_add_u32 s8, s8, 0x100000
	s_addc_u32 s9, s9, 0
	s_waitcnt vmcnt(9)
	v_cvt_pk_fp8_f32 v8, v112, v113
	v_cvt_pk_fp8_f32 v9, v114, v115
	v_cvt_pk_fp8_f32 v10, v116, v117
	v_cvt_pk_fp8_f32 v11, v118, v119
	v_and_b32_e32 v8, 0xffff, v8
	v_and_b32_e32 v10, 0xffff, v10
	v_lshl_or_b32 v140, v9, 16, v8
	v_lshl_or_b32 v141, v11, 16, v10
	global_store_dwordx2 v3, v[140:141], s[8:9]
	s_add_u32 s8, s8, 0x100000
	s_addc_u32 s9, s9, 0
	s_waitcnt vmcnt(7)
	v_cvt_pk_fp8_f32 v8, v120, v121
	v_cvt_pk_fp8_f32 v9, v122, v123
	v_cvt_pk_fp8_f32 v10, v124, v125
	v_cvt_pk_fp8_f32 v11, v126, v127
	v_and_b32_e32 v8, 0xffff, v8
	v_and_b32_e32 v10, 0xffff, v10
	v_lshl_or_b32 v142, v9, 16, v8
	v_lshl_or_b32 v143, v11, 16, v10
	global_store_dwordx2 v3, v[142:143], s[8:9]
	s_add_u32 s8, s8, 0x100000
	s_addc_u32 s9, s9, 0
	s_lshr_b32 s10, s33, 6
	s_lshl_b32 s11, s2, 3
	s_add_u32 s10, s10, s11
	s_lshl_b32 s11, s10, 2
	s_add_u32 s24, s20, s11
	s_addc_u32 s25, s21, 0
	s_load_dword s34, s[24:25], 0x0
	s_load_dword s35, s[24:25], 0x2000
	s_load_dword s36, s[24:25], 0x4000
	s_load_dword s37, s[24:25], 0x6000
	s_load_dword s38, s[24:25], 0x8000
	s_load_dword s39, s[24:25], 0xa000
	s_load_dword s40, s[24:25], 0xc000
	s_load_dword s41, s[24:25], 0xe000
	v_lshlrev_b32_e32 v5, 2, v4
	global_load_dword v5, v5, s[70:71] offset:96
	v_lshlrev_b32_e32 v6, 3, v4
	v_lshrrev_b32_e32 v7, 1, v4
	v_lshlrev_b32_e32 v7, 3, v7
	s_lshl_b32 s11, s10, 9
	s_add_u32 s26, s90, s11
	s_addc_u32 s27, s91, 0
	s_add_u32 s26, s26, 0x7c00000
	s_addc_u32 s27, s27, 0
	s_lshl_b32 s11, s10, 8
	s_add_u32 s28, s90, s11
	s_addc_u32 s29, s91, 0
	s_add_u32 s28, s28, 0x8400000
	s_addc_u32 s29, s29, 0
	s_mov_b32 s42, 0x6dc9c883
	s_mov_b32 s43, 0x3fc45f30
	s_waitcnt vmcnt(0) lgkmcnt(0)
	v_cvt_f32_i32_e32 v16, s34
	v_mul_f32_e32 v16, v5, v16
	v_cvt_f64_f32_e32 v[16:17], v16
	v_mul_f64 v[12:13], v[16:17], s[42:43]
	v_rndne_f64_e32 v[12:13], v[12:13]
	v_fma_f64 v[16:17], v[16:17], s[42:43], -v[12:13]
	v_cvt_f32_f64_e32 v17, v[16:17]
	v_cos_f32_e32 v16, v17
	v_sin_f32_e32 v17, v17
	v_cvt_f32_i32_e32 v18, s35
	v_mul_f32_e32 v18, v5, v18
	v_cvt_f64_f32_e32 v[18:19], v18
	v_mul_f64 v[12:13], v[18:19], s[42:43]
	v_rndne_f64_e32 v[12:13], v[12:13]
	v_fma_f64 v[18:19], v[18:19], s[42:43], -v[12:13]
	v_cvt_f32_f64_e32 v19, v[18:19]
	v_cos_f32_e32 v18, v19
	v_sin_f32_e32 v19, v19
	v_cvt_f32_i32_e32 v20, s36
	v_mul_f32_e32 v20, v5, v20
	v_cvt_f64_f32_e32 v[20:21], v20
	v_mul_f64 v[12:13], v[20:21], s[42:43]
	v_rndne_f64_e32 v[12:13], v[12:13]
	v_fma_f64 v[20:21], v[20:21], s[42:43], -v[12:13]
	v_cvt_f32_f64_e32 v21, v[20:21]
	v_cos_f32_e32 v20, v21
	v_sin_f32_e32 v21, v21
	v_cvt_f32_i32_e32 v22, s37
	v_mul_f32_e32 v22, v5, v22
	v_cvt_f64_f32_e32 v[22:23], v22
	v_mul_f64 v[12:13], v[22:23], s[42:43]
	v_rndne_f64_e32 v[12:13], v[12:13]
	v_fma_f64 v[22:23], v[22:23], s[42:43], -v[12:13]
	v_cvt_f32_f64_e32 v23, v[22:23]
	v_cos_f32_e32 v22, v23
	v_sin_f32_e32 v23, v23
	v_cvt_f32_i32_e32 v24, s38
	v_mul_f32_e32 v24, v5, v24
	v_cvt_f64_f32_e32 v[24:25], v24
	v_mul_f64 v[12:13], v[24:25], s[42:43]
	v_rndne_f64_e32 v[12:13], v[12:13]
	v_fma_f64 v[24:25], v[24:25], s[42:43], -v[12:13]
	v_cvt_f32_f64_e32 v25, v[24:25]
	v_cos_f32_e32 v24, v25
	v_sin_f32_e32 v25, v25
	v_cvt_f32_i32_e32 v26, s39
	v_mul_f32_e32 v26, v5, v26
	v_cvt_f64_f32_e32 v[26:27], v26
	v_mul_f64 v[12:13], v[26:27], s[42:43]
	v_rndne_f64_e32 v[12:13], v[12:13]
	v_fma_f64 v[26:27], v[26:27], s[42:43], -v[12:13]
	v_cvt_f32_f64_e32 v27, v[26:27]
	v_cos_f32_e32 v26, v27
	v_sin_f32_e32 v27, v27
	v_cvt_f32_i32_e32 v28, s40
	v_mul_f32_e32 v28, v5, v28
	v_cvt_f64_f32_e32 v[28:29], v28
	v_mul_f64 v[12:13], v[28:29], s[42:43]
	v_rndne_f64_e32 v[12:13], v[12:13]
	v_fma_f64 v[28:29], v[28:29], s[42:43], -v[12:13]
	v_cvt_f32_f64_e32 v29, v[28:29]
	v_cos_f32_e32 v28, v29
	v_sin_f32_e32 v29, v29
	v_cvt_f32_i32_e32 v30, s41
	v_mul_f32_e32 v30, v5, v30
	v_cvt_f64_f32_e32 v[30:31], v30
	v_mul_f64 v[12:13], v[30:31], s[42:43]
	v_rndne_f64_e32 v[12:13], v[12:13]
	v_fma_f64 v[30:31], v[30:31], s[42:43], -v[12:13]
	v_cvt_f32_f64_e32 v31, v[30:31]
	v_cos_f32_e32 v30, v31
	v_sin_f32_e32 v31, v31
	s_nop 1
	global_store_dwordx2 v6, v[16:17], s[26:27]
	s_add_u32 s26, s26, 0x100000
	s_addc_u32 s27, s27, 0
	global_store_dwordx2 v6, v[18:19], s[26:27]
	s_add_u32 s26, s26, 0x100000
	s_addc_u32 s27, s27, 0
	global_store_dwordx2 v6, v[20:21], s[26:27]
	s_add_u32 s26, s26, 0x100000
	s_addc_u32 s27, s27, 0
	global_store_dwordx2 v6, v[22:23], s[26:27]
	s_add_u32 s26, s26, 0x100000
	s_addc_u32 s27, s27, 0
	global_store_dwordx2 v6, v[24:25], s[26:27]
	s_add_u32 s26, s26, 0x100000
	s_addc_u32 s27, s27, 0
	global_store_dwordx2 v6, v[26:27], s[26:27]
	s_add_u32 s26, s26, 0x100000
	s_addc_u32 s27, s27, 0
	global_store_dwordx2 v6, v[28:29], s[26:27]
	s_add_u32 s26, s26, 0x100000
	s_addc_u32 s27, s27, 0
	global_store_dwordx2 v6, v[30:31], s[26:27]
	s_mov_b32 exec_lo, 0x55555555
	s_mov_b32 exec_hi, 0x55555555
	s_nop 1
	global_store_dwordx2 v7, v[16:17], s[28:29]
	s_add_u32 s28, s28, 0x80000
	s_addc_u32 s29, s29, 0
	global_store_dwordx2 v7, v[18:19], s[28:29]
	s_add_u32 s28, s28, 0x80000
	s_addc_u32 s29, s29, 0
	global_store_dwordx2 v7, v[20:21], s[28:29]
	s_add_u32 s28, s28, 0x80000
	s_addc_u32 s29, s29, 0
	global_store_dwordx2 v7, v[22:23], s[28:29]
	s_add_u32 s28, s28, 0x80000
	s_addc_u32 s29, s29, 0
	global_store_dwordx2 v7, v[24:25], s[28:29]
	s_add_u32 s28, s28, 0x80000
	s_addc_u32 s29, s29, 0
	global_store_dwordx2 v7, v[26:27], s[28:29]
	s_add_u32 s28, s28, 0x80000
	s_addc_u32 s29, s29, 0
	global_store_dwordx2 v7, v[28:29], s[28:29]
	s_add_u32 s28, s28, 0x80000
	s_addc_u32 s29, s29, 0
	global_store_dwordx2 v7, v[30:31], s[28:29]
	s_mov_b64 exec, -1
	s_nop 1
	v_and_b32_e32 v12, 7, v4
	v_lshrrev_b32_e32 v13, 3, v4
	v_lshlrev_b32_e32 v14, 4, v12
	s_mov_b32 s10, 0x5a000
	v_mul_lo_u32 v15, v13, s10
	v_add_u32_e32 v162, v15, v14
	v_add_u32_e32 v163, 0xb400, v162
	v_add_u32_e32 v164, 0x16800, v162
	v_add_u32_e32 v165, 0x21c00, v162
	v_add_u32_e32 v166, 0x2d000, v162
	v_add_u32_e32 v167, 0x38400, v162
	v_add_u32_e32 v168, 0x43800, v162
	v_add_u32_e32 v169, 0x4ec00, v162
	v_lshlrev_b32_e32 v14, 14, v12
	v_lshl_add_u32 v170, v13, 3, v14
	v_add_u32_e32 v171, 0x1000, v170
	v_add_u32_e32 v172, 0x2000, v170
	v_add_u32_e32 v173, 0x3000, v170
	s_mov_b32 s44, 0x42800000
	s_mov_b32 s45, 0x42800000
	s_lshr_b32 s10, s33, 6
	s_lshl_b32 s11, s2, 3
	s_add_u32 s46, s10, s11
	s_add_u32 s64, s90, 0x4000000
	s_addc_u32 s65, s91, 0
	s_cmpk_ge_u32 s46, 0x680
	s_cbranch_scc1 .Lp0c_four
; #define LAS __attribute__((address_space(3)))
; __device__ __forceinline__ void transpose_item_fp8(const float* W, int N, unsigned char* W8, int pitch, int kofs, int k0, int n_src, int n_dst, float scale, LAS float* scr, int lane) {
;     const int r8 = lane >> 3, c4 = lane & 7;
;     f32x4 v[8];
; #pragma unroll
;     for (int i = 0; i < 8; ++i) v[i] = *(const f32x4*)(W + (size_t)(k0 + r8 + 8 * i) * N + n_src + 4 * c4);
; #pragma unroll
;     for (int i = 0; i < 8; ++i) { LAS float* d = scr + (r8 + 8 * i) * 33 + 4 * c4; d[0] = v[i][0]; d[1] = v[i][1]; d[2] = v[i][2]; d[3] = v[i][3]; }
;     asm volatile("s_waitcnt lgkmcnt(0)" ::: "memory");
;     const int n = lane & 31, cp = lane >> 5;
; #pragma unroll
;     for (int q = 0; q < 2; ++q) { const int ck = (2 * cp + q) * 16; const LAS float* sp = scr + ck * 33 + n; u32x4 o;
; #pragma unroll
;         for (int w = 0; w < 4; ++w) o[w] = pack_fp8x4(sp[(4 * w) * 33] * scale, sp[(4 * w + 1) * 33] * scale, sp[(4 * w + 2) * 33] * scale, sp[(4 * w + 3) * 33] * scale);
;         *(u32x4*)(W8 + (size_t)(n_dst + n) * pitch + kofs + k0 + ck) = o; }
; __global__ void __launch_bounds__(512, 2) hybrid_fwd(Args a) {
;     ...
;         constexpr int I_IN = (D / 64) * (DIN / 32);
;         for (int it = gw; it < I_IN; it += NGW) { const int nb = it % (DIN / 32), kb = it / (DIN / 32);
;             if ((a.fp8mask >> (nb >> 3)) & 1ull) transpose_item_fp8(a.w_in, DIN, (unsigned char*)WinT, 4096, 0, 64 * kb, gemm_col_to_orig(32 * nb), 32 * nb, W8_SCALE, scr, lane);
	s_add_u32 s47, s46, 0x0
	s_mul_hi_u32 s48, s47, 0xb60b61
	s_mul_i32 s49, s48, 0x168
	s_sub_u32 s49, s47, s49
	s_lshl_b32 s50, s48, 1
	s_lshr_b32 s51, s49, 3
	s_and_b32 s52, s49, 7
	s_and_b32 s53, s52, 3
	s_lshr_b32 s54, s52, 2
	s_lshl_b32 s55, s53, 6
	s_lshl_b32 s56, s54, 5
	s_add_u32 s55, s55, s56
	s_bfe_u32 s56, s52, 0x10001
	s_lshl_b32 s56, s56, 7
	s_and_b32 s57, s52, 1
	s_lshl_b32 s57, s57, 5
	s_add_u32 s56, s56, s57
	s_lshl_b32 s57, s54, 6
	s_add_u32 s56, s56, s57
	s_lshl_b32 s57, s52, 5
	s_sub_u32 s58, s51, 9
	s_cmp_lt_u32 s58, 12
	s_cselect_b32 s57, s56, s57
	s_cmp_lt_u32 s51, 5
	s_cselect_b32 s57, s55, s57
	s_lshl_b32 s58, s51, 8
	s_add_u32 s57, s57, s58
	s_mul_i32 s58, s50, 0x2d0000
	s_lshl_b32 s57, s57, 2
	s_add_u32 s58, s58, s57
	s_add_u32 s60, s22, s58
	s_addc_u32 s61, s23, 0
	s_lshl_b32 s58, s49, 17
	s_lshl_b32 s59, s50, 6
	s_add_u32 s58, s58, s59
	s_add_u32 s74, s64, s58
	s_addc_u32 s75, s65, 0
	global_load_dwordx4 v[64:67], v162, s[60:61] nt
	global_load_dwordx4 v[68:71], v163, s[60:61] nt
	global_load_dwordx4 v[72:75], v164, s[60:61] nt
	global_load_dwordx4 v[76:79], v165, s[60:61] nt
	global_load_dwordx4 v[80:83], v166, s[60:61] nt
	global_load_dwordx4 v[84:87], v167, s[60:61] nt
	global_load_dwordx4 v[88:91], v168, s[60:61] nt
	global_load_dwordx4 v[92:95], v169, s[60:61] nt
	s_add_u32 s47, s46, 0x0
	s_mul_hi_u32 s48, s47, 0xb60b61
	s_mul_i32 s49, s48, 0x168
	s_sub_u32 s49, s47, s49
	s_lshl_b32 s50, s48, 1
	s_or_b32 s50, s50, 1
	s_lshr_b32 s51, s49, 3
	s_and_b32 s52, s49, 7
	s_and_b32 s53, s52, 3
	s_lshr_b32 s54, s52, 2
	s_lshl_b32 s55, s53, 6
	s_lshl_b32 s56, s54, 5
	s_add_u32 s55, s55, s56
	s_bfe_u32 s56, s52, 0x10001
	s_lshl_b32 s56, s56, 7
	s_and_b32 s57, s52, 1
	s_lshl_b32 s57, s57, 5
	s_add_u32 s56, s56, s57
	s_lshl_b32 s57, s54, 6
	s_add_u32 s56, s56, s57
	s_lshl_b32 s57, s52, 5
	s_sub_u32 s58, s51, 9
	s_cmp_lt_u32 s58, 12
	s_cselect_b32 s57, s56, s57
	s_cmp_lt_u32 s51, 5
	s_cselect_b32 s57, s55, s57
	s_lshl_b32 s58, s51, 8
	s_add_u32 s57, s57, s58
	s_mul_i32 s58, s50, 0x2d0000
	s_lshl_b32 s57, s57, 2
	s_add_u32 s58, s58, s57
	s_add_u32 s60, s22, s58
	s_addc_u32 s61, s23, 0
	s_lshl_b32 s58, s49, 17
	s_lshl_b32 s59, s50, 6
	s_add_u32 s58, s58, s59
	s_add_u32 s76, s64, s58
	s_addc_u32 s77, s65, 0
	global_load_dwordx4 v[96:99], v162, s[60:61] nt
	global_load_dwordx4 v[100:103], v163, s[60:61] nt
	global_load_dwordx4 v[104:107], v164, s[60:61] nt
	global_load_dwordx4 v[108:111], v165, s[60:61] nt
	global_load_dwordx4 v[112:115], v166, s[60:61] nt
	global_load_dwordx4 v[116:119], v167, s[60:61] nt
	global_load_dwordx4 v[120:123], v168, s[60:61] nt
	global_load_dwordx4 v[124:127], v169, s[60:61] nt
	s_add_u32 s47, s46, 0x800
	s_mul_hi_u32 s48, s47, 0xb60b61
	s_mul_i32 s49, s48, 0x168
	s_sub_u32 s49, s47, s49
	s_lshl_b32 s50, s48, 1
	s_lshr_b32 s51, s49, 3
	s_and_b32 s52, s49, 7
	s_and_b32 s53, s52, 3
	s_lshr_b32 s54, s52, 2
	s_lshl_b32 s55, s53, 6
	s_lshl_b32 s56, s54, 5
	s_add_u32 s55, s55, s56
	s_bfe_u32 s56, s52, 0x10001
	s_lshl_b32 s56, s56, 7
	s_and_b32 s57, s52, 1
	s_lshl_b32 s57, s57, 5
	s_add_u32 s56, s56, s57
	s_lshl_b32 s57, s54, 6
	s_add_u32 s56, s56, s57
	s_lshl_b32 s57, s52, 5
	s_sub_u32 s58, s51, 9
	s_cmp_lt_u32 s58, 12
	s_cselect_b32 s57, s56, s57
	s_cmp_lt_u32 s51, 5
	s_cselect_b32 s57, s55, s57
	s_lshl_b32 s58, s51, 8
	s_add_u32 s57, s57, s58
	s_mul_i32 s58, s50, 0x2d0000
	s_lshl_b32 s57, s57, 2
	s_add_u32 s58, s58, s57
	s_add_u32 s60, s22, s58
	s_addc_u32 s61, s23, 0
	s_lshl_b32 s58, s49, 17
	s_lshl_b32 s59, s50, 6
	s_add_u32 s58, s58, s59
	s_add_u32 s78, s64, s58
	s_addc_u32 s79, s65, 0
	global_load_dwordx4 v[128:131], v162, s[60:61] nt
	global_load_dwordx4 v[132:135], v163, s[60:61] nt
	global_load_dwordx4 v[136:139], v164, s[60:61] nt
	global_load_dwordx4 v[140:143], v165, s[60:61] nt
	global_load_dwordx4 v[144:147], v166, s[60:61] nt
	global_load_dwordx4 v[148:151], v167, s[60:61] nt
	global_load_dwordx4 v[152:155], v168, s[60:61] nt
	global_load_dwordx4 v[156:159], v169, s[60:61] nt
	s_waitcnt vmcnt(16)
	v_pk_mul_f32 v[64:65], v[64:65], s[44:45]
	v_pk_mul_f32 v[66:67], v[66:67], s[44:45]
	v_pk_mul_f32 v[68:69], v[68:69], s[44:45]
	v_pk_mul_f32 v[70:71], v[70:71], s[44:45]
	v_pk_mul_f32 v[72:73], v[72:73], s[44:45]
	v_pk_mul_f32 v[74:75], v[74:75], s[44:45]
	v_pk_mul_f32 v[76:77], v[76:77], s[44:45]
	v_pk_mul_f32 v[78:79], v[78:79], s[44:45]
	v_pk_mul_f32 v[80:81], v[80:81], s[44:45]
	v_pk_mul_f32 v[82:83], v[82:83], s[44:45]
	v_pk_mul_f32 v[84:85], v[84:85], s[44:45]
	v_pk_mul_f32 v[86:87], v[86:87], s[44:45]
	v_pk_mul_f32 v[88:89], v[88:89], s[44:45]
	v_pk_mul_f32 v[90:91], v[90:91], s[44:45]
	v_pk_mul_f32 v[92:93], v[92:93], s[44:45]
	v_pk_mul_f32 v[94:95], v[94:95], s[44:45]
	v_cvt_pk_fp8_f32 v8, v64, v68
	v_cvt_pk_fp8_f32 v9, v72, v76
	v_cvt_pk_fp8_f32 v10, v80, v84
	v_cvt_pk_fp8_f32 v11, v88, v92
	v_and_b32_e32 v8, 0xffff, v8
	v_and_b32_e32 v10, 0xffff, v10
	v_lshl_or_b32 v176, v9, 16, v8
	v_lshl_or_b32 v177, v11, 16, v10
	global_store_dwordx2 v170, v[176:177], s[74:75]
	v_cvt_pk_fp8_f32 v8, v65, v69
	v_cvt_pk_fp8_f32 v9, v73, v77
	v_cvt_pk_fp8_f32 v10, v81, v85
	v_cvt_pk_fp8_f32 v11, v89, v93
	v_and_b32_e32 v8, 0xffff, v8
	v_and_b32_e32 v10, 0xffff, v10
	v_lshl_or_b32 v178, v9, 16, v8
	v_lshl_or_b32 v179, v11, 16, v10
	global_store_dwordx2 v171, v[178:179], s[74:75]
	v_cvt_pk_fp8_f32 v8, v66, v70
	v_cvt_pk_fp8_f32 v9, v74, v78
	v_cvt_pk_fp8_f32 v10, v82, v86
	v_cvt_pk_fp8_f32 v11, v90, v94
	v_and_b32_e32 v8, 0xffff, v8
	v_and_b32_e32 v10, 0xffff, v10
	v_lshl_or_b32 v180, v9, 16, v8
	v_lshl_or_b32 v181, v11, 16, v10
	global_store_dwordx2 v172, v[180:181], s[74:75]
	v_cvt_pk_fp8_f32 v8, v67, v71
; #define LAS __attribute__((address_space(3)))
; __device__ __forceinline__ void transpose_item_fp8(const float* W, int N, unsigned char* W8, int pitch, int kofs, int k0, int n_src, int n_dst, float scale, LAS float* scr, int lane) {
;     const int r8 = lane >> 3, c4 = lane & 7;
;     f32x4 v[8];
; #pragma unroll
;     for (int i = 0; i < 8; ++i) v[i] = *(const f32x4*)(W + (size_t)(k0 + r8 + 8 * i) * N + n_src + 4 * c4);
; #pragma unroll
;     for (int i = 0; i < 8; ++i) { LAS float* d = scr + (r8 + 8 * i) * 33 + 4 * c4; d[0] = v[i][0]; d[1] = v[i][1]; d[2] = v[i][2]; d[3] = v[i][3]; }
;     asm volatile("s_waitcnt lgkmcnt(0)" ::: "memory");
;     const int n = lane & 31, cp = lane >> 5;
; #pragma unroll
;     for (int q = 0; q < 2; ++q) { const int ck = (2 * cp + q) * 16; const LAS float* sp = scr + ck * 33 + n; u32x4 o;
; #pragma unroll
;         for (int w = 0; w < 4; ++w) o[w] = pack_fp8x4(sp[(4 * w) * 33] * scale, sp[(4 * w + 1) * 33] * scale, sp[(4 * w + 2) * 33] * scale, sp[(4 * w + 3) * 33] * scale);
;         *(u32x4*)(W8 + (size_t)(n_dst + n) * pitch + kofs + k0 + ck) = o; }
	v_cvt_pk_fp8_f32 v9, v75, v79
	v_cvt_pk_fp8_f32 v10, v83, v87
	v_cvt_pk_fp8_f32 v11, v91, v95
	v_and_b32_e32 v8, 0xffff, v8
	v_and_b32_e32 v10, 0xffff, v10
	v_lshl_or_b32 v182, v9, 16, v8
	v_lshl_or_b32 v183, v11, 16, v10
	global_store_dwordx2 v173, v[182:183], s[74:75]
	s_add_u32 s47, s46, 0x800
	s_mul_hi_u32 s48, s47, 0xb60b61
	s_mul_i32 s49, s48, 0x168
	s_sub_u32 s49, s47, s49
	s_lshl_b32 s50, s48, 1
	s_or_b32 s50, s50, 1
	s_lshr_b32 s51, s49, 3
	s_and_b32 s52, s49, 7
	s_and_b32 s53, s52, 3
	s_lshr_b32 s54, s52, 2
	s_lshl_b32 s55, s53, 6
	s_lshl_b32 s56, s54, 5
	s_add_u32 s55, s55, s56
	s_bfe_u32 s56, s52, 0x10001
	s_lshl_b32 s56, s56, 7
	s_and_b32 s57, s52, 1
	s_lshl_b32 s57, s57, 5
	s_add_u32 s56, s56, s57
	s_lshl_b32 s57, s54, 6
	s_add_u32 s56, s56, s57
	s_lshl_b32 s57, s52, 5
	s_sub_u32 s58, s51, 9
	s_cmp_lt_u32 s58, 12
	s_cselect_b32 s57, s56, s57
	s_cmp_lt_u32 s51, 5
	s_cselect_b32 s57, s55, s57
	s_lshl_b32 s58, s51, 8
	s_add_u32 s57, s57, s58
	s_mul_i32 s58, s50, 0x2d0000
	s_lshl_b32 s57, s57, 2
	s_add_u32 s58, s58, s57
	s_add_u32 s60, s22, s58
	s_addc_u32 s61, s23, 0
	s_lshl_b32 s58, s49, 17
	s_lshl_b32 s59, s50, 6
	s_add_u32 s58, s58, s59
	s_add_u32 s74, s64, s58
	s_addc_u32 s75, s65, 0
	global_load_dwordx4 v[64:67], v162, s[60:61] nt
	global_load_dwordx4 v[68:71], v163, s[60:61] nt
	global_load_dwordx4 v[72:75], v164, s[60:61] nt
	global_load_dwordx4 v[76:79], v165, s[60:61] nt
	global_load_dwordx4 v[80:83], v166, s[60:61] nt
	global_load_dwordx4 v[84:87], v167, s[60:61] nt
	global_load_dwordx4 v[88:91], v168, s[60:61] nt
	global_load_dwordx4 v[92:95], v169, s[60:61] nt
	s_waitcnt vmcnt(20)
	v_pk_mul_f32 v[96:97], v[96:97], s[44:45]
	v_pk_mul_f32 v[98:99], v[98:99], s[44:45]
	v_pk_mul_f32 v[100:101], v[100:101], s[44:45]
	v_pk_mul_f32 v[102:103], v[102:103], s[44:45]
	v_pk_mul_f32 v[104:105], v[104:105], s[44:45]
	v_pk_mul_f32 v[106:107], v[106:107], s[44:45]
	v_pk_mul_f32 v[108:109], v[108:109], s[44:45]
	v_pk_mul_f32 v[110:111], v[110:111], s[44:45]
	v_pk_mul_f32 v[112:113], v[112:113], s[44:45]
	v_pk_mul_f32 v[114:115], v[114:115], s[44:45]
	v_pk_mul_f32 v[116:117], v[116:117], s[44:45]
	v_pk_mul_f32 v[118:119], v[118:119], s[44:45]
	v_pk_mul_f32 v[120:121], v[120:121], s[44:45]
	v_pk_mul_f32 v[122:123], v[122:123], s[44:45]
	v_pk_mul_f32 v[124:125], v[124:125], s[44:45]
	v_pk_mul_f32 v[126:127], v[126:127], s[44:45]
	v_cvt_pk_fp8_f32 v8, v96, v100
	v_cvt_pk_fp8_f32 v9, v104, v108
	v_cvt_pk_fp8_f32 v10, v112, v116
	v_cvt_pk_fp8_f32 v11, v120, v124
	v_and_b32_e32 v8, 0xffff, v8
	v_and_b32_e32 v10, 0xffff, v10
	v_lshl_or_b32 v184, v9, 16, v8
	v_lshl_or_b32 v185, v11, 16, v10
	global_store_dwordx2 v170, v[184:185], s[76:77]
	v_cvt_pk_fp8_f32 v8, v97, v101
	v_cvt_pk_fp8_f32 v9, v105, v109
	v_cvt_pk_fp8_f32 v10, v113, v117
	v_cvt_pk_fp8_f32 v11, v121, v125
	v_and_b32_e32 v8, 0xffff, v8
	v_and_b32_e32 v10, 0xffff, v10
	v_lshl_or_b32 v186, v9, 16, v8
	v_lshl_or_b32 v187, v11, 16, v10
	global_store_dwordx2 v171, v[186:187], s[76:77]
	v_cvt_pk_fp8_f32 v8, v98, v102
	v_cvt_pk_fp8_f32 v9, v106, v110
	v_cvt_pk_fp8_f32 v10, v114, v118
	v_cvt_pk_fp8_f32 v11, v122, v126
	v_and_b32_e32 v8, 0xffff, v8
	v_and_b32_e32 v10, 0xffff, v10
	v_lshl_or_b32 v188, v9, 16, v8
	v_lshl_or_b32 v189, v11, 16, v10
	global_store_dwordx2 v172, v[188:189], s[76:77]
	v_cvt_pk_fp8_f32 v8, v99, v103
	v_cvt_pk_fp8_f32 v9, v107, v111
	v_cvt_pk_fp8_f32 v10, v115, v119
	v_cvt_pk_fp8_f32 v11, v123, v127
	v_and_b32_e32 v8, 0xffff, v8
	v_and_b32_e32 v10, 0xffff, v10
	v_lshl_or_b32 v190, v9, 16, v8
	v_lshl_or_b32 v191, v11, 16, v10
	global_store_dwordx2 v173, v[190:191], s[76:77]
	s_add_u32 s47, s46, 0x1000
	s_mul_hi_u32 s48, s47, 0xb60b61
	s_mul_i32 s49, s48, 0x168
	s_sub_u32 s49, s47, s49
	s_lshl_b32 s50, s48, 1
	s_lshr_b32 s51, s49, 3
	s_and_b32 s52, s49, 7
	s_and_b32 s53, s52, 3
	s_lshr_b32 s54, s52, 2
	s_lshl_b32 s55, s53, 6
	s_lshl_b32 s56, s54, 5
	s_add_u32 s55, s55, s56
	s_bfe_u32 s56, s52, 0x10001
	s_lshl_b32 s56, s56, 7
	s_and_b32 s57, s52, 1
	s_lshl_b32 s57, s57, 5
	s_add_u32 s56, s56, s57
	s_lshl_b32 s57, s54, 6
	s_add_u32 s56, s56, s57
	s_lshl_b32 s57, s52, 5
	s_sub_u32 s58, s51, 9
	s_cmp_lt_u32 s58, 12
	s_cselect_b32 s57, s56, s57
	s_cmp_lt_u32 s51, 5
	s_cselect_b32 s57, s55, s57
	s_lshl_b32 s58, s51, 8
	s_add_u32 s57, s57, s58
	s_mul_i32 s58, s50, 0x2d0000
	s_lshl_b32 s57, s57, 2
	s_add_u32 s58, s58, s57
	s_add_u32 s60, s22, s58
	s_addc_u32 s61, s23, 0
	s_lshl_b32 s58, s49, 17
	s_lshl_b32 s59, s50, 6
	s_add_u32 s58, s58, s59
	s_add_u32 s76, s64, s58
	s_addc_u32 s77, s65, 0
	global_load_dwordx4 v[96:99], v162, s[60:61] nt
	global_load_dwordx4 v[100:103], v163, s[60:61] nt
	global_load_dwordx4 v[104:107], v164, s[60:61] nt
	global_load_dwordx4 v[108:111], v165, s[60:61] nt
	global_load_dwordx4 v[112:115], v166, s[60:61] nt
	global_load_dwordx4 v[116:119], v167, s[60:61] nt
	global_load_dwordx4 v[120:123], v168, s[60:61] nt
	global_load_dwordx4 v[124:127], v169, s[60:61] nt
	s_waitcnt vmcnt(24)
; #define LAS __attribute__((address_space(3)))
; __device__ __forceinline__ void transpose_item_fp8(const float* W, int N, unsigned char* W8, int pitch, int kofs, int k0, int n_src, int n_dst, float scale, LAS float* scr, int lane) {
;     const int r8 = lane >> 3, c4 = lane & 7;
;     f32x4 v[8];
; #pragma unroll
;     for (int i = 0; i < 8; ++i) v[i] = *(const f32x4*)(W + (size_t)(k0 + r8 + 8 * i) * N + n_src + 4 * c4);
; #pragma unroll
;     for (int i = 0; i < 8; ++i) { LAS float* d = scr + (r8 + 8 * i) * 33 + 4 * c4; d[0] = v[i][0]; d[1] = v[i][1]; d[2] = v[i][2]; d[3] = v[i][3]; }
;     asm volatile("s_waitcnt lgkmcnt(0)" ::: "memory");
;     const int n = lane & 31, cp = lane >> 5;
; #pragma unroll
;     for (int q = 0; q < 2; ++q) { const int ck = (2 * cp + q) * 16; const LAS float* sp = scr + ck * 33 + n; u32x4 o;
; #pragma unroll
;         for (int w = 0; w < 4; ++w) o[w] = pack_fp8x4(sp[(4 * w) * 33] * scale, sp[(4 * w + 1) * 33] * scale, sp[(4 * w + 2) * 33] * scale, sp[(4 * w + 3) * 33] * scale);
;         *(u32x4*)(W8 + (size_t)(n_dst + n) * pitch + kofs + k0 + ck) = o; }
	v_pk_mul_f32 v[128:129], v[128:129], s[44:45]
	v_pk_mul_f32 v[130:131], v[130:131], s[44:45]
	v_pk_mul_f32 v[132:133], v[132:133], s[44:45]
	v_pk_mul_f32 v[134:135], v[134:135], s[44:45]
	v_pk_mul_f32 v[136:137], v[136:137], s[44:45]
	v_pk_mul_f32 v[138:139], v[138:139], s[44:45]
	v_pk_mul_f32 v[140:141], v[140:141], s[44:45]
	v_pk_mul_f32 v[142:143], v[142:143], s[44:45]
	v_pk_mul_f32 v[144:145], v[144:145], s[44:45]
	v_pk_mul_f32 v[146:147], v[146:147], s[44:45]
	v_pk_mul_f32 v[148:149], v[148:149], s[44:45]
	v_pk_mul_f32 v[150:151], v[150:151], s[44:45]
	v_pk_mul_f32 v[152:153], v[152:153], s[44:45]
	v_pk_mul_f32 v[154:155], v[154:155], s[44:45]
	v_pk_mul_f32 v[156:157], v[156:157], s[44:45]
	v_pk_mul_f32 v[158:159], v[158:159], s[44:45]
	v_cvt_pk_fp8_f32 v8, v128, v132
	v_cvt_pk_fp8_f32 v9, v136, v140
	v_cvt_pk_fp8_f32 v10, v144, v148
	v_cvt_pk_fp8_f32 v11, v152, v156
	v_and_b32_e32 v8, 0xffff, v8
	v_and_b32_e32 v10, 0xffff, v10
	v_lshl_or_b32 v176, v9, 16, v8
	v_lshl_or_b32 v177, v11, 16, v10
	global_store_dwordx2 v170, v[176:177], s[78:79]
	v_cvt_pk_fp8_f32 v8, v129, v133
	v_cvt_pk_fp8_f32 v9, v137, v141
	v_cvt_pk_fp8_f32 v10, v145, v149
	v_cvt_pk_fp8_f32 v11, v153, v157
	v_and_b32_e32 v8, 0xffff, v8
	v_and_b32_e32 v10, 0xffff, v10
	v_lshl_or_b32 v178, v9, 16, v8
	v_lshl_or_b32 v179, v11, 16, v10
	global_store_dwordx2 v171, v[178:179], s[78:79]
	v_cvt_pk_fp8_f32 v8, v130, v134
	v_cvt_pk_fp8_f32 v9, v138, v142
	v_cvt_pk_fp8_f32 v10, v146, v150
	v_cvt_pk_fp8_f32 v11, v154, v158
	v_and_b32_e32 v8, 0xffff, v8
	v_and_b32_e32 v10, 0xffff, v10
	v_lshl_or_b32 v180, v9, 16, v8
	v_lshl_or_b32 v181, v11, 16, v10
	global_store_dwordx2 v172, v[180:181], s[78:79]
	v_cvt_pk_fp8_f32 v8, v131, v135
	v_cvt_pk_fp8_f32 v9, v139, v143
	v_cvt_pk_fp8_f32 v10, v147, v151
	v_cvt_pk_fp8_f32 v11, v155, v159
	v_and_b32_e32 v8, 0xffff, v8
	v_and_b32_e32 v10, 0xffff, v10
	v_lshl_or_b32 v182, v9, 16, v8
	v_lshl_or_b32 v183, v11, 16, v10
	global_store_dwordx2 v173, v[182:183], s[78:79]
	s_add_u32 s47, s46, 0x1000
	s_mul_hi_u32 s48, s47, 0xb60b61
	s_mul_i32 s49, s48, 0x168
	s_sub_u32 s49, s47, s49
	s_lshl_b32 s50, s48, 1
	s_or_b32 s50, s50, 1
	s_lshr_b32 s51, s49, 3
	s_and_b32 s52, s49, 7
	s_and_b32 s53, s52, 3
	s_lshr_b32 s54, s52, 2
	s_lshl_b32 s55, s53, 6
	s_lshl_b32 s56, s54, 5
	s_add_u32 s55, s55, s56
	s_bfe_u32 s56, s52, 0x10001
	s_lshl_b32 s56, s56, 7
	s_and_b32 s57, s52, 1
	s_lshl_b32 s57, s57, 5
	s_add_u32 s56, s56, s57
	s_lshl_b32 s57, s54, 6
	s_add_u32 s56, s56, s57
	s_lshl_b32 s57, s52, 5
	s_sub_u32 s58, s51, 9
	s_cmp_lt_u32 s58, 12
	s_cselect_b32 s57, s56, s57
	s_cmp_lt_u32 s51, 5
	s_cselect_b32 s57, s55, s57
	s_lshl_b32 s58, s51, 8
	s_add_u32 s57, s57, s58
	s_mul_i32 s58, s50, 0x2d0000
	s_lshl_b32 s57, s57, 2
	s_add_u32 s58, s58, s57
	s_add_u32 s60, s22, s58
	s_addc_u32 s61, s23, 0
	s_lshl_b32 s58, s49, 17
	s_lshl_b32 s59, s50, 6
	s_add_u32 s58, s58, s59
	s_add_u32 s78, s64, s58
	s_addc_u32 s79, s65, 0
	global_load_dwordx4 v[128:131], v162, s[60:61] nt
	global_load_dwordx4 v[132:135], v163, s[60:61] nt
	global_load_dwordx4 v[136:139], v164, s[60:61] nt
	global_load_dwordx4 v[140:143], v165, s[60:61] nt
	global_load_dwordx4 v[144:147], v166, s[60:61] nt
	global_load_dwordx4 v[148:151], v167, s[60:61] nt
	global_load_dwordx4 v[152:155], v168, s[60:61] nt
	global_load_dwordx4 v[156:159], v169, s[60:61] nt
	s_waitcnt vmcnt(24)
	v_pk_mul_f32 v[64:65], v[64:65], s[44:45]
	v_pk_mul_f32 v[66:67], v[66:67], s[44:45]
	v_pk_mul_f32 v[68:69], v[68:69], s[44:45]
	v_pk_mul_f32 v[70:71], v[70:71], s[44:45]
	v_pk_mul_f32 v[72:73], v[72:73], s[44:45]
	v_pk_mul_f32 v[74:75], v[74:75], s[44:45]
	v_pk_mul_f32 v[76:77], v[76:77], s[44:45]
	v_pk_mul_f32 v[78:79], v[78:79], s[44:45]
	v_pk_mul_f32 v[80:81], v[80:81], s[44:45]
	v_pk_mul_f32 v[82:83], v[82:83], s[44:45]
	v_pk_mul_f32 v[84:85], v[84:85], s[44:45]
	v_pk_mul_f32 v[86:87], v[86:87], s[44:45]
	v_pk_mul_f32 v[88:89], v[88:89], s[44:45]
	v_pk_mul_f32 v[90:91], v[90:91], s[44:45]
	v_pk_mul_f32 v[92:93], v[92:93], s[44:45]
	v_pk_mul_f32 v[94:95], v[94:95], s[44:45]
	v_cvt_pk_fp8_f32 v8, v64, v68
	v_cvt_pk_fp8_f32 v9, v72, v76
	v_cvt_pk_fp8_f32 v10, v80, v84
	v_cvt_pk_fp8_f32 v11, v88, v92
	v_and_b32_e32 v8, 0xffff, v8
	v_and_b32_e32 v10, 0xffff, v10
	v_lshl_or_b32 v184, v9, 16, v8
	v_lshl_or_b32 v185, v11, 16, v10
	global_store_dwordx2 v170, v[184:185], s[74:75]
	v_cvt_pk_fp8_f32 v8, v65, v69
	v_cvt_pk_fp8_f32 v9, v73, v77
	v_cvt_pk_fp8_f32 v10, v81, v85
	v_cvt_pk_fp8_f32 v11, v89, v93
	v_and_b32_e32 v8, 0xffff, v8
	v_and_b32_e32 v10, 0xffff, v10
	v_lshl_or_b32 v186, v9, 16, v8
	v_lshl_or_b32 v187, v11, 16, v10
	global_store_dwordx2 v171, v[186:187], s[74:75]
	v_cvt_pk_fp8_f32 v8, v66, v70
	v_cvt_pk_fp8_f32 v9, v74, v78
	v_cvt_pk_fp8_f32 v10, v82, v86
	v_cvt_pk_fp8_f32 v11, v90, v94
	v_and_b32_e32 v8, 0xffff, v8
	v_and_b32_e32 v10, 0xffff, v10
	v_lshl_or_b32 v188, v9, 16, v8
	v_lshl_or_b32 v189, v11, 16, v10
	global_store_dwordx2 v172, v[188:189], s[74:75]
	v_cvt_pk_fp8_f32 v8, v67, v71
	v_cvt_pk_fp8_f32 v9, v75, v79
	v_cvt_pk_fp8_f32 v10, v83, v87
	v_cvt_pk_fp8_f32 v11, v91, v95
	v_and_b32_e32 v8, 0xffff, v8
	v_and_b32_e32 v10, 0xffff, v10
	v_lshl_or_b32 v190, v9, 16, v8
	v_lshl_or_b32 v191, v11, 16, v10
	global_store_dwordx2 v173, v[190:191], s[74:75]
	s_waitcnt vmcnt(16)
; #define LAS __attribute__((address_space(3)))
; __device__ __forceinline__ void transpose_item_fp8(const float* W, int N, unsigned char* W8, int pitch, int kofs, int k0, int n_src, int n_dst, float scale, LAS float* scr, int lane) {
;     const int r8 = lane >> 3, c4 = lane & 7;
;     f32x4 v[8];
; #pragma unroll
;     for (int i = 0; i < 8; ++i) v[i] = *(const f32x4*)(W + (size_t)(k0 + r8 + 8 * i) * N + n_src + 4 * c4);
; #pragma unroll
;     for (int i = 0; i < 8; ++i) { LAS float* d = scr + (r8 + 8 * i) * 33 + 4 * c4; d[0] = v[i][0]; d[1] = v[i][1]; d[2] = v[i][2]; d[3] = v[i][3]; }
;     asm volatile("s_waitcnt lgkmcnt(0)" ::: "memory");
;     const int n = lane & 31, cp = lane >> 5;
; #pragma unroll
;     for (int q = 0; q < 2; ++q) { const int ck = (2 * cp + q) * 16; const LAS float* sp = scr + ck * 33 + n; u32x4 o;
; #pragma unroll
;         for (int w = 0; w < 4; ++w) o[w] = pack_fp8x4(sp[(4 * w) * 33] * scale, sp[(4 * w + 1) * 33] * scale, sp[(4 * w + 2) * 33] * scale, sp[(4 * w + 3) * 33] * scale);
;         *(u32x4*)(W8 + (size_t)(n_dst + n) * pitch + kofs + k0 + ck) = o; }
	v_pk_mul_f32 v[96:97], v[96:97], s[44:45]
	v_pk_mul_f32 v[98:99], v[98:99], s[44:45]
	v_pk_mul_f32 v[100:101], v[100:101], s[44:45]
	v_pk_mul_f32 v[102:103], v[102:103], s[44:45]
	v_pk_mul_f32 v[104:105], v[104:105], s[44:45]
	v_pk_mul_f32 v[106:107], v[106:107], s[44:45]
	v_pk_mul_f32 v[108:109], v[108:109], s[44:45]
	v_pk_mul_f32 v[110:111], v[110:111], s[44:45]
	v_pk_mul_f32 v[112:113], v[112:113], s[44:45]
	v_pk_mul_f32 v[114:115], v[114:115], s[44:45]
	v_pk_mul_f32 v[116:117], v[116:117], s[44:45]
	v_pk_mul_f32 v[118:119], v[118:119], s[44:45]
	v_pk_mul_f32 v[120:121], v[120:121], s[44:45]
	v_pk_mul_f32 v[122:123], v[122:123], s[44:45]
	v_pk_mul_f32 v[124:125], v[124:125], s[44:45]
	v_pk_mul_f32 v[126:127], v[126:127], s[44:45]
	v_cvt_pk_fp8_f32 v8, v96, v100
	v_cvt_pk_fp8_f32 v9, v104, v108
	v_cvt_pk_fp8_f32 v10, v112, v116
	v_cvt_pk_fp8_f32 v11, v120, v124
	v_and_b32_e32 v8, 0xffff, v8
	v_and_b32_e32 v10, 0xffff, v10
	v_lshl_or_b32 v176, v9, 16, v8
	v_lshl_or_b32 v177, v11, 16, v10
	global_store_dwordx2 v170, v[176:177], s[76:77]
	v_cvt_pk_fp8_f32 v8, v97, v101
	v_cvt_pk_fp8_f32 v9, v105, v109
	v_cvt_pk_fp8_f32 v10, v113, v117
	v_cvt_pk_fp8_f32 v11, v121, v125
	v_and_b32_e32 v8, 0xffff, v8
	v_and_b32_e32 v10, 0xffff, v10
	v_lshl_or_b32 v178, v9, 16, v8
	v_lshl_or_b32 v179, v11, 16, v10
	global_store_dwordx2 v171, v[178:179], s[76:77]
	v_cvt_pk_fp8_f32 v8, v98, v102
	v_cvt_pk_fp8_f32 v9, v106, v110
	v_cvt_pk_fp8_f32 v10, v114, v118
	v_cvt_pk_fp8_f32 v11, v122, v126
	v_and_b32_e32 v8, 0xffff, v8
	v_and_b32_e32 v10, 0xffff, v10
	v_lshl_or_b32 v180, v9, 16, v8
	v_lshl_or_b32 v181, v11, 16, v10
	global_store_dwordx2 v172, v[180:181], s[76:77]
	v_cvt_pk_fp8_f32 v8, v99, v103
	v_cvt_pk_fp8_f32 v9, v107, v111
	v_cvt_pk_fp8_f32 v10, v115, v119
	v_cvt_pk_fp8_f32 v11, v123, v127
	v_and_b32_e32 v8, 0xffff, v8
	v_and_b32_e32 v10, 0xffff, v10
	v_lshl_or_b32 v182, v9, 16, v8
	v_lshl_or_b32 v183, v11, 16, v10
	global_store_dwordx2 v173, v[182:183], s[76:77]
	s_waitcnt vmcnt(8)
	v_pk_mul_f32 v[128:129], v[128:129], s[44:45]
	v_pk_mul_f32 v[130:131], v[130:131], s[44:45]
	v_pk_mul_f32 v[132:133], v[132:133], s[44:45]
	v_pk_mul_f32 v[134:135], v[134:135], s[44:45]
	v_pk_mul_f32 v[136:137], v[136:137], s[44:45]
	v_pk_mul_f32 v[138:139], v[138:139], s[44:45]
	v_pk_mul_f32 v[140:141], v[140:141], s[44:45]
	v_pk_mul_f32 v[142:143], v[142:143], s[44:45]
	v_pk_mul_f32 v[144:145], v[144:145], s[44:45]
	v_pk_mul_f32 v[146:147], v[146:147], s[44:45]
	v_pk_mul_f32 v[148:149], v[148:149], s[44:45]
	v_pk_mul_f32 v[150:151], v[150:151], s[44:45]
	v_pk_mul_f32 v[152:153], v[152:153], s[44:45]
	v_pk_mul_f32 v[154:155], v[154:155], s[44:45]
	v_pk_mul_f32 v[156:157], v[156:157], s[44:45]
	v_pk_mul_f32 v[158:159], v[158:159], s[44:45]
	v_cvt_pk_fp8_f32 v8, v128, v132
	v_cvt_pk_fp8_f32 v9, v136, v140
	v_cvt_pk_fp8_f32 v10, v144, v148
	v_cvt_pk_fp8_f32 v11, v152, v156
	v_and_b32_e32 v8, 0xffff, v8
	v_and_b32_e32 v10, 0xffff, v10
	v_lshl_or_b32 v184, v9, 16, v8
	v_lshl_or_b32 v185, v11, 16, v10
	global_store_dwordx2 v170, v[184:185], s[78:79]
	v_cvt_pk_fp8_f32 v8, v129, v133
	v_cvt_pk_fp8_f32 v9, v137, v141
	v_cvt_pk_fp8_f32 v10, v145, v149
	v_cvt_pk_fp8_f32 v11, v153, v157
	v_and_b32_e32 v8, 0xffff, v8
	v_and_b32_e32 v10, 0xffff, v10
	v_lshl_or_b32 v186, v9, 16, v8
	v_lshl_or_b32 v187, v11, 16, v10
	global_store_dwordx2 v171, v[186:187], s[78:79]
	v_cvt_pk_fp8_f32 v8, v130, v134
	v_cvt_pk_fp8_f32 v9, v138, v142
	v_cvt_pk_fp8_f32 v10, v146, v150
	v_cvt_pk_fp8_f32 v11, v154, v158
	v_and_b32_e32 v8, 0xffff, v8
	v_and_b32_e32 v10, 0xffff, v10
	v_lshl_or_b32 v188, v9, 16, v8
	v_lshl_or_b32 v189, v11, 16, v10
	global_store_dwordx2 v172, v[188:189], s[78:79]
	v_cvt_pk_fp8_f32 v8, v131, v135
	v_cvt_pk_fp8_f32 v9, v139, v143
	v_cvt_pk_fp8_f32 v10, v147, v151
	v_cvt_pk_fp8_f32 v11, v155, v159
	v_and_b32_e32 v8, 0xffff, v8
	v_and_b32_e32 v10, 0xffff, v10
	v_lshl_or_b32 v190, v9, 16, v8
	v_lshl_or_b32 v191, v11, 16, v10
	global_store_dwordx2 v173, v[190:191], s[78:79]
	s_branch .Lp0c_end

; __device__ __forceinline__ void own_barrier(unsigned* cnt, unsigned G) {
;     asm volatile("s_waitcnt vmcnt(0) lgkmcnt(0)" ::: "memory");
;     __syncthreads();
;     if (threadIdx.x == 0) {
;         __builtin_amdgcn_fence(__ATOMIC_RELEASE, "agent"); asm volatile("s_waitcnt vmcnt(0)" ::: "memory");
;         unsigned target;
;         if ((G & 7u) == 0u) { target = 8u;
;             const unsigned old = __hip_atomic_fetch_add(cnt + 64 * (1 + (blockIdx.x & 7)), 1u, __ATOMIC_RELAXED, __HIP_MEMORY_SCOPE_AGENT);
;             if (old + 1u == (G >> 3)) __hip_atomic_fetch_add(cnt, 1u, __ATOMIC_RELAXED, __HIP_MEMORY_SCOPE_AGENT); }
;         else { target = G; __hip_atomic_fetch_add(cnt, 1u, __ATOMIC_RELAXED, __HIP_MEMORY_SCOPE_AGENT); }
.LBB0_340:
	s_waitcnt vmcnt(0) lgkmcnt(0)
	s_barrier
	s_mov_b64 s[4:5], exec
	v_readlane_b32 s8, v242, 4
	v_readlane_b32 s9, v242, 5
	s_and_b64 s[8:9], s[4:5], s[8:9]
	s_mov_b64 exec, s[8:9]
	s_cbranch_execz .LBB0_366
	s_cmp_lg_u32 s92, 0x100
	s_cbranch_scc1 .Lseam2_orig
	buffer_wbl2 sc1
	s_waitcnt vmcnt(0)
	s_mov_b64 exec, -1
	v_mbcnt_lo_u32_b32 v246, -1, 0
	v_mbcnt_hi_u32_b32 v246, -1, v246
	v_lshlrev_b32_e32 v247, 2, v246
	v_add_u32_e32 v247, 0x8e08000, v247
	v_and_b32_e32 v248, 7, v246
	v_lshlrev_b32_e32 v248, 2, v248
	v_add_u32_e32 v248, 0x8e08000, v248
	global_load_dword v249, v247, s[90:91] sc1
	global_load_dword v250, v247, s[90:91] offset:256 sc1
	global_load_dword v251, v247, s[90:91] offset:512 sc1
	global_load_dword v252, v247, s[90:91] offset:768 sc1
	global_load_dword v253, v248, s[90:91] sc1
	s_mov_b64 exec, 1
	v_mov_b32_e32 v1, 0x8e02000
	v_mov_b32_e32 v2, 1
	global_atomic_add v2, v1, v2, s[90:91] sc0
	s_lshl_b32 s100, s2, 12
	s_add_u32 s100, s100, 0x8e10000
	v_mov_b32_e32 v1, s100
	s_waitcnt vmcnt(0)
	s_mov_b64 exec, -1
	v_xor_b32_e32 v249, v249, v253
	v_xor_b32_e32 v250, v250, v253
	v_xor_b32_e32 v251, v251, v253
	v_xor_b32_e32 v252, v252, v253
	v_or3_b32 v249, v249, v250, v251
	v_or_b32_e32 v249, v249, v252
	v_readlane_b32 s100, v253, 0
	s_lshl_b32 s100, 1, s100
	s_mov_b32 vcc_lo, s100
	v_readlane_b32 s100, v253, 1
	s_lshl_b32 s100, 1, s100
	s_or_b32 vcc_lo, vcc_lo, s100
	v_readlane_b32 s100, v253, 2
	s_lshl_b32 s100, 1, s100
	s_or_b32 vcc_lo, vcc_lo, s100
	v_readlane_b32 s100, v253, 3
	s_lshl_b32 s100, 1, s100
	s_or_b32 vcc_lo, vcc_lo, s100
	v_readlane_b32 s100, v253, 4
	s_lshl_b32 s100, 1, s100
	s_or_b32 vcc_lo, vcc_lo, s100
	v_readlane_b32 s100, v253, 5
	s_lshl_b32 s100, 1, s100
	s_or_b32 vcc_lo, vcc_lo, s100
	v_readlane_b32 s100, v253, 6
	s_lshl_b32 s100, 1, s100
	s_or_b32 vcc_lo, vcc_lo, s100
	v_readlane_b32 s100, v253, 7
	s_lshl_b32 s100, 1, s100
	s_or_b32 vcc_lo, vcc_lo, s100
	s_cmp_eq_u32 vcc_lo, 0xff
	s_cselect_b32 m0, 1, 0
	v_cmp_ne_u32_e32 vcc, 0, v249
	s_cmp_eq_u64 vcc, 0
	s_cselect_b32 s100, 1, 0
	s_and_b32 s100, s100, m0
	s_mov_b64 exec, 1
	v_writelane_b32 v246, s100, 0
	v_readfirstlane_b32 s100, v2
	s_cmp_eq_u32 s100, 0xff
	s_cbranch_scc0 .Lseam2_wait
	s_mov_b64 exec, -1
	v_mbcnt_lo_u32_b32 v243, -1, 0
	v_mbcnt_hi_u32_b32 v243, -1, v243
	v_lshlrev_b32_e32 v243, 12, v243
	v_add_u32_e32 v243, 0x8e10000, v243
	v_mov_b32_e32 v244, 2
	global_store_dword v243, v244, s[90:91] sc1
	v_add_u32_e32 v243, 0x40000, v243
	global_store_dword v243, v244, s[90:91] sc1
	v_add_u32_e32 v243, 0x40000, v243
	global_store_dword v243, v244, s[90:91] sc1
	v_add_u32_e32 v243, 0x40000, v243
	global_store_dword v243, v244, s[90:91] sc1
	s_mov_b64 exec, 1
	s_branch .Lseam2_done

; __device__ __forceinline__ void own_barrier(unsigned* cnt, unsigned G) {
;     asm volatile("s_waitcnt vmcnt(0) lgkmcnt(0)" ::: "memory");
;     __syncthreads();
;     if (threadIdx.x == 0) {
;         __builtin_amdgcn_fence(__ATOMIC_RELEASE, "agent"); asm volatile("s_waitcnt vmcnt(0)" ::: "memory");
;         unsigned target;
;         if ((G & 7u) == 0u) { target = 8u;
;             const unsigned old = __hip_atomic_fetch_add(cnt + 64 * (1 + (blockIdx.x & 7)), 1u, __ATOMIC_RELAXED, __HIP_MEMORY_SCOPE_AGENT);
;             if (old + 1u == (G >> 3)) __hip_atomic_fetch_add(cnt, 1u, __ATOMIC_RELAXED, __HIP_MEMORY_SCOPE_AGENT); }
;         else { target = G; __hip_atomic_fetch_add(cnt, 1u, __ATOMIC_RELAXED, __HIP_MEMORY_SCOPE_AGENT); }
.LBB0_431:
	s_waitcnt vmcnt(0) lgkmcnt(0)
	s_waitcnt vmcnt(0)
	s_barrier
	s_and_saveexec_b64 s[4:5], s[62:63]
	s_cbranch_execz .LBB0_457
	s_cmp_lg_u32 s92, 0x100
	s_cbranch_scc1 .Lseam4_orig
	v_readlane_b32 s100, v246, 0
	s_cmp_eq_u32 s100, 1
	s_cbranch_scc1 .Lseam4_nowb
	buffer_wbl2 sc1
	s_waitcnt vmcnt(0)
.Lseam4_nowb:
	v_mov_b32_e32 v1, 0x8e04000
	v_mov_b32_e32 v2, 1
	global_atomic_add v2, v1, v2, s[90:91] sc0
	s_lshl_b32 s100, s2, 12
	s_add_u32 s100, s100, 0x8e10000
	v_mov_b32_e32 v1, s100
	s_waitcnt vmcnt(0)
	v_readfirstlane_b32 s100, v2
	s_cmp_eq_u32 s100, 0xff
	s_cbranch_scc0 .Lseam4_wait
	s_mov_b64 exec, -1
	v_mbcnt_lo_u32_b32 v243, -1, 0
	v_mbcnt_hi_u32_b32 v243, -1, v243
	v_lshlrev_b32_e32 v243, 12, v243
	v_add_u32_e32 v243, 0x8e10000, v243
	v_mov_b32_e32 v244, 4
	global_store_dword v243, v244, s[90:91] sc1
	v_add_u32_e32 v243, 0x40000, v243
	global_store_dword v243, v244, s[90:91] sc1
	v_add_u32_e32 v243, 0x40000, v243
	global_store_dword v243, v244, s[90:91] sc1
	v_add_u32_e32 v243, 0x40000, v243
	global_store_dword v243, v244, s[90:91] sc1
	s_mov_b64 exec, 1
	s_branch .Lseam4_done

; __device__ __forceinline__ void own_barrier(unsigned* cnt, unsigned G) {
;     ...
;         while (__hip_atomic_load(cnt, __ATOMIC_RELAXED, __HIP_MEMORY_SCOPE_AGENT) < target && ++spins < (1u << 22)) __builtin_amdgcn_s_sleep(1);
;         __builtin_amdgcn_fence(__ATOMIC_ACQUIRE, "agent"); asm volatile("s_waitcnt vmcnt(0)" ::: "memory");
;     }
;     __syncthreads();
.Lseam4_done:
	v_readlane_b32 s100, v246, 0
	s_cmp_eq_u32 s100, 1
	s_cbranch_scc0 .Lseam4_invl2
	buffer_inv sc0
	s_waitcnt vmcnt(0)
	s_branch .Lseam4_join

; __device__ __forceinline__ void own_barrier(unsigned* cnt, unsigned G) {
;     asm volatile("s_waitcnt vmcnt(0) lgkmcnt(0)" ::: "memory");
;     __syncthreads();
;     if (threadIdx.x == 0) {
;         __builtin_amdgcn_fence(__ATOMIC_RELEASE, "agent"); asm volatile("s_waitcnt vmcnt(0)" ::: "memory");
;         unsigned target;
;         if ((G & 7u) == 0u) { target = 8u;
;             const unsigned old = __hip_atomic_fetch_add(cnt + 64 * (1 + (blockIdx.x & 7)), 1u, __ATOMIC_RELAXED, __HIP_MEMORY_SCOPE_AGENT);
;             if (old + 1u == (G >> 3)) __hip_atomic_fetch_add(cnt, 1u, __ATOMIC_RELAXED, __HIP_MEMORY_SCOPE_AGENT); }
;         else { target = G; __hip_atomic_fetch_add(cnt, 1u, __ATOMIC_RELAXED, __HIP_MEMORY_SCOPE_AGENT); }
.LBB0_499:
	s_waitcnt vmcnt(0) lgkmcnt(0)
	s_waitcnt lgkmcnt(0)
	s_barrier
	s_and_saveexec_b64 s[4:5], s[62:63]
	s_cbranch_execz .LBB0_525
	s_cmp_lg_u32 s92, 0x100
	s_cbranch_scc1 .Lseam5_orig
	v_readlane_b32 s100, v246, 0
	s_cmp_eq_u32 s100, 1
	s_cbranch_scc1 .Lseam5_nowb
	buffer_wbl2 sc1
	s_waitcnt vmcnt(0)
.Lseam5_nowb:
	v_mov_b32_e32 v1, 0x8e05000
	v_mov_b32_e32 v2, 1
	global_atomic_add v2, v1, v2, s[90:91] sc0
	s_lshl_b32 s100, s2, 12
	s_add_u32 s100, s100, 0x8e10000
	v_mov_b32_e32 v1, s100
	s_waitcnt vmcnt(0)
	v_readfirstlane_b32 s100, v2
	s_cmp_eq_u32 s100, 0xff
	s_cbranch_scc0 .Lseam5_wait
	s_mov_b64 exec, -1
	v_mbcnt_lo_u32_b32 v243, -1, 0
	v_mbcnt_hi_u32_b32 v243, -1, v243
	v_lshlrev_b32_e32 v243, 12, v243
	v_add_u32_e32 v243, 0x8e10000, v243
	v_mov_b32_e32 v244, 5
	global_store_dword v243, v244, s[90:91] sc1
	v_add_u32_e32 v243, 0x40000, v243
	global_store_dword v243, v244, s[90:91] sc1
	v_add_u32_e32 v243, 0x40000, v243
	global_store_dword v243, v244, s[90:91] sc1
	v_add_u32_e32 v243, 0x40000, v243
	global_store_dword v243, v244, s[90:91] sc1
	s_mov_b64 exec, 1
	s_branch .Lseam5_done
